# grid-sync poll interval s_sleep 1 to 24 on top of v16 (attention loop restructure + 4-deep ring, scan o-wave load masking, PEER head-rank rewrite)
# speedup vs baseline: 1.0199x; 1.0025x over previous
.LBB0_38:
	s_sleep 24
	global_load_dword v3, v1, s[6:7] offset:32 sc1
	s_waitcnt vmcnt(0)
	v_and_b32_e32 v3, 0xffff0000, v3
	v_cmp_ne_u32_e32 vcc, v3, v2
	s_or_b64 s[8:9], vcc, s[8:9]
	s_andn2_b64 exec, exec, s[8:9]
	s_cbranch_execnz .LBB0_38

.LBB0_330:
	s_sleep 24
	global_load_dword v3, v1, s[4:5] offset:32 sc1
	s_waitcnt vmcnt(0)
	v_and_b32_e32 v3, 0xffff0000, v3
	v_cmp_ne_u32_e32 vcc, v3, v2
	s_or_b64 s[6:7], vcc, s[6:7]
	s_andn2_b64 exec, exec, s[6:7]
	s_cbranch_execnz .LBB0_330

.LBB0_798:
	s_sleep 24
	global_load_dword v4, v2, s[4:5] offset:32 sc1
	s_waitcnt vmcnt(0)
	v_and_b32_e32 v4, 0xffff0000, v4
	v_cmp_ne_u32_e32 vcc, v4, v3
	s_or_b64 s[6:7], vcc, s[6:7]
	s_andn2_b64 exec, exec, s[6:7]
	s_cbranch_execnz .LBB0_798

.LBB0_991:
	s_sleep 24
	global_load_dword v2, v0, s[2:3] offset:32 sc1
	s_waitcnt vmcnt(0)
	v_and_b32_e32 v2, 0xffff0000, v2
	v_cmp_ne_u32_e32 vcc, v2, v1
	s_or_b64 s[4:5], vcc, s[4:5]
	s_andn2_b64 exec, exec, s[4:5]
	s_cbranch_execnz .LBB0_991
